# attention: next tile's LDS-DMA issue moved from the loop top into the V-fragment read latency shadow (off the per-tile dependent chain)
# baseline (speedup 1.0000x reference)
.LBB0_235:
	v_sub_f32_e32 v80, v80, v145
	v_exp_f32_e32 v80, v80
	v_sub_f32_e32 v81, v81, v145
	v_exp_f32_e32 v81, v81
	v_sub_f32_e32 v82, v82, v145
	v_exp_f32_e32 v82, v82
	v_sub_f32_e32 v83, v83, v145
	v_exp_f32_e32 v83, v83
	v_sub_f32_e32 v84, v84, v145
	v_add_f32_e32 v188, 0, v80
	v_exp_f32_e32 v84, v84
	v_sub_f32_e32 v85, v85, v145
	v_add_f32_e32 v188, v81, v188
	v_exp_f32_e32 v85, v85
	v_sub_f32_e32 v86, v86, v145
	v_add_f32_e32 v188, v82, v188
	v_exp_f32_e32 v86, v86
	v_sub_f32_e32 v87, v87, v145
	v_add_f32_e32 v188, v83, v188
	v_exp_f32_e32 v87, v87
	v_sub_f32_e32 v88, v88, v145
	v_add_f32_e32 v188, v84, v188
	v_exp_f32_e32 v88, v88
	v_sub_f32_e32 v89, v89, v145
	v_add_f32_e32 v188, v85, v188
	v_exp_f32_e32 v89, v89
	v_sub_f32_e32 v90, v90, v145
	v_add_f32_e32 v188, v86, v188
	v_exp_f32_e32 v90, v90
	v_sub_f32_e32 v91, v91, v145
	v_add_f32_e32 v188, v87, v188
	v_exp_f32_e32 v91, v91
	v_sub_f32_e32 v92, v92, v145
	v_add_f32_e32 v188, v88, v188
	v_exp_f32_e32 v92, v92
	v_sub_f32_e32 v93, v93, v145
	v_add_f32_e32 v188, v89, v188
	v_exp_f32_e32 v93, v93
	v_sub_f32_e32 v94, v94, v145
	v_add_f32_e32 v188, v90, v188
	v_exp_f32_e32 v94, v94
	v_sub_f32_e32 v95, v95, v145
	v_add_f32_e32 v188, v91, v188
	v_exp_f32_e32 v95, v95
	v_sub_f32_e32 v64, v64, v145
	v_add_f32_e32 v188, v92, v188
	v_exp_f32_e32 v189, v64
	v_sub_f32_e32 v64, v65, v145
	v_add_f32_e32 v188, v93, v188
	v_exp_f32_e32 v190, v64
	v_sub_f32_e32 v64, v66, v145
	v_add_f32_e32 v188, v94, v188
	v_exp_f32_e32 v191, v64
	v_sub_f32_e32 v64, v67, v145
	v_add_f32_e32 v188, v95, v188
	v_exp_f32_e32 v192, v64
	v_sub_f32_e32 v65, v68, v145
	v_add_f32_e32 v64, v189, v188
	v_exp_f32_e32 v188, v65
	v_sub_f32_e32 v65, v69, v145
	v_add_f32_e32 v64, v190, v64
	v_exp_f32_e32 v193, v65
	v_sub_f32_e32 v65, v70, v145
	v_add_f32_e32 v64, v191, v64
	v_exp_f32_e32 v194, v65
	v_sub_f32_e32 v65, v71, v145
	v_add_f32_e32 v64, v192, v64
	v_exp_f32_e32 v195, v65
	v_sub_f32_e32 v65, v72, v145
	v_add_f32_e32 v64, v188, v64
	v_exp_f32_e32 v196, v65
	v_sub_f32_e32 v65, v73, v145
	v_add_f32_e32 v64, v193, v64
	v_exp_f32_e32 v197, v65
	v_sub_f32_e32 v65, v74, v145
	v_add_f32_e32 v64, v194, v64
	v_exp_f32_e32 v198, v65
	v_sub_f32_e32 v65, v75, v145
	v_add_f32_e32 v64, v195, v64
	v_exp_f32_e32 v199, v65
	v_sub_f32_e32 v65, v76, v145
	v_add_f32_e32 v64, v196, v64
	v_exp_f32_e32 v200, v65
	v_sub_f32_e32 v65, v77, v145
	v_add_f32_e32 v64, v197, v64
	v_exp_f32_e32 v201, v65
	v_sub_f32_e32 v65, v78, v145
	v_add_f32_e32 v64, v198, v64
	v_exp_f32_e32 v202, v65
	v_sub_f32_e32 v65, v79, v145
	v_add_f32_e32 v64, v199, v64
	v_exp_f32_e32 v79, v65
	v_add_f32_e32 v64, v200, v64
	v_add_f32_e32 v64, v201, v64
	v_subrev_u32_e32 v151, s26, v176
	v_subrev_u32_e32 v187, s26, v174
	v_add_f32_e32 v64, v202, v64
	v_add_u32_e32 v204, s54, v181
	v_add_f32_e32 v212, v79, v64
	v_cvt_pk_bf16_f32 v64, v80, v81
	v_cvt_pk_bf16_f32 v65, v82, v83
	v_cvt_pk_bf16_f32 v66, v84, v85
	v_cvt_pk_bf16_f32 v67, v86, v87
	v_cvt_pk_bf16_f32 v68, v88, v89
	v_cvt_pk_bf16_f32 v69, v90, v91
	v_cvt_pk_bf16_f32 v70, v92, v93
	v_add_u32_e32 v92, v204, v187
	v_add_u32_e32 v151, v204, v151
	v_cvt_pk_bf16_f32 v71, v94, v95
	v_cvt_pk_bf16_f32 v72, v189, v190
	v_cvt_pk_bf16_f32 v73, v191, v192
	v_cvt_pk_bf16_f32 v74, v188, v193
	v_cvt_pk_bf16_f32 v75, v194, v195
	v_cvt_pk_bf16_f32 v76, v196, v197
	v_cvt_pk_bf16_f32 v77, v198, v199
	v_cvt_pk_bf16_f32 v78, v200, v201
	v_cvt_pk_bf16_f32 v79, v202, v79
	ds_read_b128 v[80:83], v92 offset:16384
	ds_read_b128 v[84:87], v92 offset:20480
	ds_read_b128 v[88:91], v92 offset:24576
	ds_read_b128 v[92:95], v92 offset:28672
	ds_read_b128 v[188:191], v151 offset:16384
	ds_read_b128 v[192:195], v151 offset:20480
	ds_read_b128 v[196:199], v151 offset:24576
	ds_read_b128 v[200:203], v151 offset:28672
	v_subrev_u32_e32 v147, s26, v180
	v_subrev_u32_e32 v149, s26, v178
	v_add_u32_e32 v149, v204, v149
	v_add_u32_e32 v147, v204, v147
	ds_read_b128 v[208:211], v149 offset:16384
	ds_read_b128 v[214:217], v149 offset:20480
	ds_read_b128 v[230:233], v149 offset:24576
	ds_read_b128 v[234:237], v149 offset:28672
	ds_read_b128 v[238:241], v147 offset:16384
	ds_read_b128 v[242:245], v147 offset:20480
	ds_read_b128 v[246:249], v147 offset:24576
	ds_read_b128 v[204:207], v147 offset:28672
	s_add_i32 s99, s45, -1
	s_cmp_ge_u32 s99, s15
	s_cbranch_scc1 .Latt_dma_done
	s_mul_hi_u32 s27, s50, 0xaaaaaaab
	s_lshr_b32 s27, s27, 1
	s_mul_i32 s27, s27, 0x18000
	s_sub_i32 s27, s54, s27
	s_add_i32 s27, s27, s28
	v_lshl_add_u64 v[250:251], s[48:49], 0, v[152:153]
	s_add_i32 m0, s27, 0x10000
	s_nop 0
	global_load_lds_dwordx4 v[250:251], off
	v_lshl_add_u64 v[250:251], s[48:49], 0, v[168:169]
	s_add_i32 m0, s27, 0x14000
	s_nop 0
	global_load_lds_dwordx4 v[250:251], off
	v_lshl_add_u64 v[250:251], s[48:49], 0, v[170:171]
	s_add_i32 m0, s27, 0x10400
	s_nop 0
	global_load_lds_dwordx4 v[250:251], off
	v_lshl_add_u64 v[250:251], s[48:49], 0, v[154:155]
	s_add_i32 m0, s27, 0x14400
	s_nop 0
	global_load_lds_dwordx4 v[250:251], off
.Latt_dma_done:
	s_setprio 1
	s_waitcnt lgkmcnt(0)
	v_mfma_f32_32x32x16_bf16 v[48:63], v[80:83], v[64:67], v[48:63]
	v_add_f32_e32 v143, v143, v212
	v_mfma_f32_32x32x16_bf16 v[48:63], v[188:191], v[68:71], v[48:63]
	v_mfma_f32_32x32x16_bf16 v[48:63], v[208:211], v[72:75], v[48:63]
	v_mfma_f32_32x32x16_bf16 v[48:63], v[238:241], v[76:79], v[48:63]
	v_mfma_f32_32x32x16_bf16 v[32:47], v[84:87], v[64:67], v[32:47]
	v_mfma_f32_32x32x16_bf16 v[32:47], v[192:195], v[68:71], v[32:47]
	v_mfma_f32_32x32x16_bf16 v[32:47], v[214:217], v[72:75], v[32:47]
	v_mfma_f32_32x32x16_bf16 v[32:47], v[242:245], v[76:79], v[32:47]
	v_mfma_f32_32x32x16_bf16 v[16:31], v[88:91], v[64:67], v[16:31]
	v_mfma_f32_32x32x16_bf16 v[16:31], v[196:199], v[68:71], v[16:31]
	v_mfma_f32_32x32x16_bf16 v[16:31], v[230:233], v[72:75], v[16:31]
	v_mfma_f32_32x32x16_bf16 v[16:31], v[246:249], v[76:79], v[16:31]
	v_mfma_f32_32x32x16_bf16 v[0:15], v[92:95], v[64:67], v[0:15]
	v_mfma_f32_32x32x16_bf16 v[0:15], v[200:203], v[68:71], v[0:15]
	v_mfma_f32_32x32x16_bf16 v[0:15], v[234:237], v[72:75], v[0:15]
	v_mfma_f32_32x32x16_bf16 v[0:15], v[204:207], v[76:79], v[0:15]
	s_setprio 0

; __device__ __forceinline__ void unit(const Ctx& F, int b, int h, int qb, const bf16_t* Q, const bf16_t* Kg, const bf16_t* VT, bf16_t* O, float lam) {
;     ...
;         __builtin_amdgcn_s_barrier(); asm volatile("" ::: "memory");
;         if (j + 2 < NT) ATT_DMA(j + 2, ((j + 2) % 3) * BUF);
;         if (j <= cq) { const int bo = (j % 3) * BUF; ATT_S(bo); ATT_PV(bo); }
.LBB0_241:
	s_barrier
	s_add_i32 s26, s45, -1
.LBB0_243:
	s_cmp_gt_i32 s26, s52
	s_cbranch_scc1 .LBB0_236
	s_mul_hi_u32 s26, s55, 0xaaaaaaab
	s_lshr_b32 s26, s26, 1
	s_mul_i32 s26, s26, 0x18000
	v_subrev_u32_e32 v72, s26, v179
	v_subrev_u32_e32 v73, s26, v177
	v_subrev_u32_e32 v74, s26, v175
	v_subrev_u32_e32 v64, s26, v173
	v_add_u32_e32 v75, s54, v182
	v_add_u32_e32 v68, v75, v64
	v_add_u32_e32 v74, v75, v74
	v_add_u32_e32 v73, v75, v73
	v_add_u32_e32 v72, v75, v72
	ds_read_b128 v[64:67], v68
	ds_read_b128 v[68:71], v68 offset:8192
	ds_read_b128 v[188:191], v74
	ds_read_b128 v[192:195], v74 offset:8192
	ds_read_b128 v[196:199], v73
	ds_read_b128 v[200:203], v73 offset:8192
	ds_read_b128 v[208:211], v72
	ds_read_b128 v[214:217], v72 offset:8192
	s_waitcnt lgkmcnt(0)
	s_setprio 1
	s_waitcnt lgkmcnt(0)
	v_mfma_f32_32x32x16_bf16 v[80:95], v[64:67], v[96:99], 0
	v_mfma_f32_32x32x16_bf16 v[80:95], v[188:191], v[100:103], v[80:95]
	v_mfma_f32_32x32x16_bf16 v[80:95], v[196:199], v[104:107], v[80:95]
	v_mfma_f32_32x32x16_bf16 v[80:95], v[208:211], v[108:111], v[80:95]
	v_mfma_f32_32x32x16_bf16 v[64:79], v[68:71], v[96:99], 0
	v_mfma_f32_32x32x16_bf16 v[64:79], v[192:195], v[100:103], v[64:79]
	v_mfma_f32_32x32x16_bf16 v[64:79], v[200:203], v[104:107], v[64:79]
	v_mfma_f32_32x32x16_bf16 v[64:79], v[214:217], v[108:111], v[64:79]
	s_setprio 0
	s_nop 10
	v_max3_f32 v147, v80, v81, v82
	v_max3_f32 v149, v64, v65, v66
	v_max3_f32 v147, v147, v83, v84
	v_max3_f32 v149, v149, v67, v68
	v_max3_f32 v147, v147, v85, v86
	v_max3_f32 v149, v149, v69, v70
	v_max3_f32 v147, v147, v87, v88
	v_max3_f32 v149, v149, v71, v72
	v_max3_f32 v147, v147, v89, v90
	v_max3_f32 v149, v149, v73, v74
	v_max3_f32 v147, v147, v91, v92
	v_max3_f32 v149, v149, v75, v76
	v_max3_f32 v147, v147, v93, v94
	v_max3_f32 v149, v149, v77, v78
	v_max3_f32 v147, v147, v95, v79
	v_max_f32_e32 v147, v147, v149
	v_mov_b32_e32 v149, v147
	s_nop 1
	v_permlane32_swap_b32_e32 v147, v149
	v_max_f32_e32 v149, v149, v149
	v_max_f32_e32 v147, v147, v147
	v_max_f32_e32 v147, v147, v149
	v_cmp_gt_f32_e32 vcc, v147, v145
	s_cbranch_vccz .LBB0_235
	v_max_f32_e32 v147, v147, v147
	v_max_f32_e32 v149, v145, v145
	v_max_f32_e32 v147, v149, v147
	v_sub_f32_e32 v145, v145, v147
	v_exp_f32_e32 v188, v145
	v_mov_b32_e32 v145, v147
	v_pk_mul_f32 v[62:63], v[62:63], v[188:189] op_sel_hi:[1,0]
	v_pk_mul_f32 v[60:61], v[60:61], v[188:189] op_sel_hi:[1,0]
	v_pk_mul_f32 v[58:59], v[58:59], v[188:189] op_sel_hi:[1,0]
	v_pk_mul_f32 v[56:57], v[56:57], v[188:189] op_sel_hi:[1,0]
	v_pk_mul_f32 v[54:55], v[54:55], v[188:189] op_sel_hi:[1,0]
	v_pk_mul_f32 v[52:53], v[52:53], v[188:189] op_sel_hi:[1,0]
	v_pk_mul_f32 v[50:51], v[50:51], v[188:189] op_sel_hi:[1,0]
	v_pk_mul_f32 v[48:49], v[48:49], v[188:189] op_sel_hi:[1,0]
	v_pk_mul_f32 v[46:47], v[46:47], v[188:189] op_sel_hi:[1,0]
	v_pk_mul_f32 v[44:45], v[44:45], v[188:189] op_sel_hi:[1,0]
	v_pk_mul_f32 v[42:43], v[42:43], v[188:189] op_sel_hi:[1,0]
	v_pk_mul_f32 v[40:41], v[40:41], v[188:189] op_sel_hi:[1,0]
	v_pk_mul_f32 v[38:39], v[38:39], v[188:189] op_sel_hi:[1,0]
	v_pk_mul_f32 v[36:37], v[36:37], v[188:189] op_sel_hi:[1,0]
	v_pk_mul_f32 v[34:35], v[34:35], v[188:189] op_sel_hi:[1,0]
	v_pk_mul_f32 v[32:33], v[32:33], v[188:189] op_sel_hi:[1,0]
	v_pk_mul_f32 v[30:31], v[30:31], v[188:189] op_sel_hi:[1,0]
	v_pk_mul_f32 v[28:29], v[28:29], v[188:189] op_sel_hi:[1,0]
	v_pk_mul_f32 v[26:27], v[26:27], v[188:189] op_sel_hi:[1,0]
	v_pk_mul_f32 v[24:25], v[24:25], v[188:189] op_sel_hi:[1,0]
	v_pk_mul_f32 v[22:23], v[22:23], v[188:189] op_sel_hi:[1,0]
	v_pk_mul_f32 v[20:21], v[20:21], v[188:189] op_sel_hi:[1,0]
	v_pk_mul_f32 v[18:19], v[18:19], v[188:189] op_sel_hi:[1,0]
	v_pk_mul_f32 v[16:17], v[16:17], v[188:189] op_sel_hi:[1,0]
	v_pk_mul_f32 v[14:15], v[14:15], v[188:189] op_sel_hi:[1,0]
	v_pk_mul_f32 v[12:13], v[12:13], v[188:189] op_sel_hi:[1,0]
	v_pk_mul_f32 v[10:11], v[10:11], v[188:189] op_sel_hi:[1,0]
	v_pk_mul_f32 v[8:9], v[8:9], v[188:189] op_sel_hi:[1,0]
	v_pk_mul_f32 v[6:7], v[6:7], v[188:189] op_sel_hi:[1,0]
	v_pk_mul_f32 v[4:5], v[4:5], v[188:189] op_sel_hi:[1,0]
	v_pk_mul_f32 v[2:3], v[2:3], v[188:189] op_sel_hi:[1,0]
	v_pk_mul_f32 v[0:1], v[0:1], v[188:189] op_sel_hi:[1,0]
	v_mul_f32_e32 v143, v143, v188
	s_branch .LBB0_235
